# P12 prompt row pass: all accesses 16 bytes per lane (lane owns 8 consecutive columns per 512-column half; y/f as dwordx4 instead of 2x dwordx2)
# speedup vs baseline: 1.0050x; 1.0050x over previous
; __device__ __forceinline__ f32x4 up4(u32x2 w) { return (f32x4){bf_lo(w.x), bf_hi(w.x), bf_lo(w.y), bf_hi(w.y)}; }
; __device__ __forceinline__ void row_pass1(const Args& a, int row_lo, int row_hi, int gw, int NGW, int lane) {
;     ...
;         for (int r = 0; r < 2; ++r) { const int row = r0 + r; if (row >= row_hi) break;
;             const float rstd = rsqrtf(rs[r] * (1.f / DM) + EPS); f32x4 v[4]; float s = 0.f;
; #pragma unroll
;             for (int j = 0; j < 4; ++j) { v[j] = xv[r][j] + up4(yv[r][j]) * rstd * gp[j]; s += (v[j][0] * v[j][0] + v[j][1] * v[j][1]) + (v[j][2] * v[j][2] + v[j][3] * v[j][3]); }
; template <bool DRYR = false>
; __device__ __forceinline__ void row_pass2(const Args& a, int row_lo, int row_hi, int gw, int NGW, int lane) {
;     ...
;     for (int r0 = row_lo + 2 * gw; r0 < row_hi; r0 += 2 * NGW) {
;         f32x4 xv[2][4]; u32x2 fv[2][4]; float rs[2];
; #pragma unroll
;         for (int r = 0; r < 2; ++r) { const int row = (r0 + r < row_hi) ? r0 + r : r0; rs[r] = rss[row];
;             const f32x4* xo = (const f32x4*)(XO + (size_t)row * DM) + lane; const u32x2* fr = (const u32x2*)(F + (size_t)row * DM) + lane;
; #pragma unroll
;             for (int j = 0; j < 4; ++j) { xv[r][j] = xo[64 * j]; fv[r][j] = fr[64 * j]; } }
; #pragma unroll
;         for (int r = 0; r < 2; ++r) { const int row = r0 + r; if (row >= row_hi) break;
;             const float rstd = rsqrtf(rs[r] * (1.f / DM) + EPS); f32x4* xo = (f32x4*)(XO + (size_t)row * DM) + lane;
; #pragma unroll
;             for (int j = 0; j < 4; ++j) { const f32x4 o = xv[r][j] + up4(fv[r][j]) * rstd * gp[j]; if (!DRYR || o[0] == 123.456f) xo[64 * j] = o; } }
.LBB0_1413:
	s_and_b64 vcc, exec, s[10:11]
	s_cbranch_vccz .LBB0_1419
	s_lshl_b32 s0, s81, 1
	s_addk_i32 s0, 0xfe00
	s_cmpk_gt_i32 s0, 0x3fff
	s_cbranch_scc1 .LBB0_1419
	s_waitcnt vmcnt(0)
	v_mov_b32_e32 v145, 0
	v_readlane_b32 s20, v252, 1
	v_readlane_b32 s21, v252, 2
	v_readlane_b32 s14, v252, 13
	v_readlane_b32 s15, v252, 14
	v_lshlrev_b32_e32 v148, 5, v176
	v_add_u32_e32 v149, 0x1000, v148
	v_mov_b32_e32 v116, 0x358637bd
	s_lshl_b32 s1, s58, 4
	s_add_i32 s4, s1, 0xfffffe00
	s_ashr_i32 s1, s0, 31
	s_lshl_b64 s[10:11], s[0:1], 12
	global_load_dwordx4 v[84:87], v148, s[14:15]
	global_load_dwordx4 v[88:91], v148, s[14:15] offset:16
	global_load_dwordx4 v[92:95], v148, s[14:15] offset:2048
	global_load_dwordx4 v[96:99], v148, s[14:15] offset:2064
	global_load_dwordx4 v[0:3], v148, s[12:13]
	global_load_dwordx4 v[4:7], v148, s[12:13] offset:16
	global_load_dwordx4 v[8:11], v148, s[12:13] offset:2048
	global_load_dwordx4 v[12:15], v148, s[12:13] offset:2064
	s_add_u32 s20, s20, s10
	s_addc_u32 s21, s21, s11
	s_add_u32 s22, s52, s10
	s_addc_u32 s23, s53, s11
	s_lshl_b64 s[10:11], s[0:1], 11
	s_add_u32 s24, s54, s10
	s_addc_u32 s25, s55, s11
	s_add_u32 s26, s24, 0xbc00000
	s_addc_u32 s27, s25, 0
	s_add_u32 s24, s24, 0xde00000
	s_addc_u32 s25, s25, 0
	s_lshl_b64 s[10:11], s[0:1], 2
	s_add_u32 s16, s54, s10
	s_addc_u32 s17, s55, s11
	s_add_u32 s18, s16, 0x2291000
	s_addc_u32 s19, s17, 0
	s_add_u32 s16, s16, 0x2280000
	s_addc_u32 s17, s17, 0
	s_lshl_b32 s98, s4, 12
	s_lshl_b32 s99, s4, 11
	s_lshl_b32 s100, s4, 2
	s_mov_b32 s3, 0x800000
.Lxo_loop:
	global_load_dwordx2 v[80:81], v145, s[16:17]
	global_load_dwordx2 v[82:83], v145, s[18:19]
	global_load_dwordx4 v[48:51], v144, s[24:25] nt
	global_load_dwordx4 v[52:55], v144, s[24:25] offset:1024 nt
	global_load_dwordx4 v[16:19], v148, s[20:21] nt
	global_load_dwordx4 v[20:23], v148, s[20:21] offset:16 nt
	global_load_dwordx4 v[24:27], v148, s[20:21] offset:2048 nt
	global_load_dwordx4 v[28:31], v148, s[20:21] offset:2064 nt
	global_load_dwordx4 v[64:67], v144, s[26:27] nt
	global_load_dwordx4 v[68:71], v144, s[26:27] offset:1024 nt
	global_load_dwordx4 v[56:59], v144, s[24:25] offset:2048 nt
	global_load_dwordx4 v[60:63], v144, s[24:25] offset:3072 nt
	global_load_dwordx4 v[32:35], v149, s[20:21] nt
	global_load_dwordx4 v[36:39], v149, s[20:21] offset:16 nt
	global_load_dwordx4 v[40:43], v149, s[20:21] offset:2048 nt
	global_load_dwordx4 v[44:47], v149, s[20:21] offset:2064 nt
	global_load_dwordx4 v[72:75], v144, s[26:27] offset:2048 nt
	global_load_dwordx4 v[76:79], v144, s[26:27] offset:3072 nt
	s_waitcnt vmcnt(8)
	v_fmamk_f32 v104, v80, 0x3a800000, v116
	v_mul_f32_e32 v105, 0x4b800000, v104
	v_cmp_gt_f32_e32 vcc, s3, v104
	s_nop 1
	v_cndmask_b32_e32 v104, v104, v105, vcc
	v_rsq_f32_e32 v104, v104
	s_nop 0
	v_mul_f32_e32 v105, 0x45800000, v104
	v_cndmask_b32_e32 v104, v104, v105, vcc
	v_fmamk_f32 v106, v82, 0x3a800000, v116
	v_mul_f32_e32 v107, 0x4b800000, v106
	v_cmp_gt_f32_e32 vcc, s3, v106
	s_nop 1
	v_cndmask_b32_e32 v106, v106, v107, vcc
	v_rsq_f32_e32 v106, v106
	s_nop 0
	v_mul_f32_e32 v107, 0x45800000, v106
	v_cndmask_b32_e32 v106, v106, v107, vcc
	v_lshlrev_b32_e32 v120, 16, v48
	v_and_b32_e32 v121, 0xffff0000, v48
	v_lshlrev_b32_e32 v122, 16, v49
	v_and_b32_e32 v123, 0xffff0000, v49
	v_lshlrev_b32_e32 v150, 16, v64
	v_and_b32_e32 v151, 0xffff0000, v64
	v_lshlrev_b32_e32 v152, 16, v65
	v_and_b32_e32 v153, 0xffff0000, v65
	v_pk_mul_f32 v[120:121], v[104:105], v[120:121] op_sel_hi:[0,1]
	v_pk_mul_f32 v[122:123], v[104:105], v[122:123] op_sel_hi:[0,1]
	v_pk_mul_f32 v[150:151], v[106:107], v[150:151] op_sel_hi:[0,1]
	v_pk_mul_f32 v[152:153], v[106:107], v[152:153] op_sel_hi:[0,1]
	v_pk_fma_f32 v[16:17], v[84:85], v[120:121], v[16:17]
	v_pk_fma_f32 v[18:19], v[86:87], v[122:123], v[18:19]
	v_pk_fma_f32 v[16:17], v[0:1], v[150:151], v[16:17]
	v_pk_fma_f32 v[18:19], v[2:3], v[152:153], v[18:19]
	v_lshlrev_b32_e32 v124, 16, v50
	v_and_b32_e32 v125, 0xffff0000, v50
	v_lshlrev_b32_e32 v126, 16, v51
	v_and_b32_e32 v127, 0xffff0000, v51
	v_lshlrev_b32_e32 v154, 16, v66
	v_and_b32_e32 v155, 0xffff0000, v66
	v_lshlrev_b32_e32 v156, 16, v67
	v_and_b32_e32 v157, 0xffff0000, v67
	v_pk_mul_f32 v[124:125], v[104:105], v[124:125] op_sel_hi:[0,1]
	v_pk_mul_f32 v[126:127], v[104:105], v[126:127] op_sel_hi:[0,1]
	v_pk_mul_f32 v[154:155], v[106:107], v[154:155] op_sel_hi:[0,1]
	v_pk_mul_f32 v[156:157], v[106:107], v[156:157] op_sel_hi:[0,1]
	v_pk_fma_f32 v[20:21], v[88:89], v[124:125], v[20:21]
	v_pk_fma_f32 v[22:23], v[90:91], v[126:127], v[22:23]
	v_pk_fma_f32 v[20:21], v[4:5], v[154:155], v[20:21]
	v_pk_fma_f32 v[22:23], v[6:7], v[156:157], v[22:23]
	v_lshlrev_b32_e32 v128, 16, v52
	v_and_b32_e32 v129, 0xffff0000, v52
	v_lshlrev_b32_e32 v130, 16, v53
	v_and_b32_e32 v131, 0xffff0000, v53
	v_lshlrev_b32_e32 v158, 16, v68
	v_and_b32_e32 v159, 0xffff0000, v68
	v_lshlrev_b32_e32 v160, 16, v69
	v_and_b32_e32 v161, 0xffff0000, v69
	v_pk_mul_f32 v[128:129], v[104:105], v[128:129] op_sel_hi:[0,1]
	v_pk_mul_f32 v[130:131], v[104:105], v[130:131] op_sel_hi:[0,1]
	v_pk_mul_f32 v[158:159], v[106:107], v[158:159] op_sel_hi:[0,1]
	v_pk_mul_f32 v[160:161], v[106:107], v[160:161] op_sel_hi:[0,1]
	v_pk_fma_f32 v[24:25], v[92:93], v[128:129], v[24:25]
	v_pk_fma_f32 v[26:27], v[94:95], v[130:131], v[26:27]
	v_pk_fma_f32 v[24:25], v[8:9], v[158:159], v[24:25]
	v_pk_fma_f32 v[26:27], v[10:11], v[160:161], v[26:27]
	v_lshlrev_b32_e32 v132, 16, v54
	v_and_b32_e32 v133, 0xffff0000, v54
	v_lshlrev_b32_e32 v134, 16, v55
	v_and_b32_e32 v135, 0xffff0000, v55
	v_lshlrev_b32_e32 v162, 16, v70
	v_and_b32_e32 v163, 0xffff0000, v70
	v_lshlrev_b32_e32 v164, 16, v71
	v_and_b32_e32 v165, 0xffff0000, v71
	v_pk_mul_f32 v[132:133], v[104:105], v[132:133] op_sel_hi:[0,1]
	v_pk_mul_f32 v[134:135], v[104:105], v[134:135] op_sel_hi:[0,1]
	v_pk_mul_f32 v[162:163], v[106:107], v[162:163] op_sel_hi:[0,1]
	v_pk_mul_f32 v[164:165], v[106:107], v[164:165] op_sel_hi:[0,1]
	v_pk_fma_f32 v[28:29], v[96:97], v[132:133], v[28:29]
	v_pk_fma_f32 v[30:31], v[98:99], v[134:135], v[30:31]
	v_pk_fma_f32 v[28:29], v[12:13], v[162:163], v[28:29]
	v_pk_fma_f32 v[30:31], v[14:15], v[164:165], v[30:31]
	global_store_dwordx4 v148, v[16:19], s[22:23] nt
	global_store_dwordx4 v148, v[20:23], s[22:23] offset:16 nt
	global_store_dwordx4 v148, v[24:27], s[22:23] offset:2048 nt
	global_store_dwordx4 v148, v[28:31], s[22:23] offset:2064 nt
	s_waitcnt vmcnt(4)
; __device__ __forceinline__ f32x4 up4(u32x2 w) { return (f32x4){bf_lo(w.x), bf_hi(w.x), bf_lo(w.y), bf_hi(w.y)}; }
; __device__ __forceinline__ void row_pass1(const Args& a, int row_lo, int row_hi, int gw, int NGW, int lane) {
;     ...
;         for (int r = 0; r < 2; ++r) { const int row = r0 + r; if (row >= row_hi) break;
;             const float rstd = rsqrtf(rs[r] * (1.f / DM) + EPS); f32x4 v[4]; float s = 0.f;
; #pragma unroll
;             for (int j = 0; j < 4; ++j) { v[j] = xv[r][j] + up4(yv[r][j]) * rstd * gp[j]; s += (v[j][0] * v[j][0] + v[j][1] * v[j][1]) + (v[j][2] * v[j][2] + v[j][3] * v[j][3]); }
; template <bool DRYR = false>
; __device__ __forceinline__ void row_pass2(const Args& a, int row_lo, int row_hi, int gw, int NGW, int lane) {
;     ...
;     for (int r0 = row_lo + 2 * gw; r0 < row_hi; r0 += 2 * NGW) {
;         f32x4 xv[2][4]; u32x2 fv[2][4]; float rs[2];
; #pragma unroll
;         for (int r = 0; r < 2; ++r) { const int row = (r0 + r < row_hi) ? r0 + r : r0; rs[r] = rss[row];
;             const f32x4* xo = (const f32x4*)(XO + (size_t)row * DM) + lane; const u32x2* fr = (const u32x2*)(F + (size_t)row * DM) + lane;
; #pragma unroll
;             for (int j = 0; j < 4; ++j) { xv[r][j] = xo[64 * j]; fv[r][j] = fr[64 * j]; } }
; #pragma unroll
;         for (int r = 0; r < 2; ++r) { const int row = r0 + r; if (row >= row_hi) break;
;             const float rstd = rsqrtf(rs[r] * (1.f / DM) + EPS); f32x4* xo = (f32x4*)(XO + (size_t)row * DM) + lane;
; #pragma unroll
;             for (int j = 0; j < 4; ++j) { const f32x4 o = xv[r][j] + up4(fv[r][j]) * rstd * gp[j]; if (!DRYR || o[0] == 123.456f) xo[64 * j] = o; } }
	v_fmamk_f32 v104, v81, 0x3a800000, v116
	v_mul_f32_e32 v105, 0x4b800000, v104
	v_cmp_gt_f32_e32 vcc, s3, v104
	s_nop 1
	v_cndmask_b32_e32 v104, v104, v105, vcc
	v_rsq_f32_e32 v104, v104
	s_nop 0
	v_mul_f32_e32 v105, 0x45800000, v104
	v_cndmask_b32_e32 v104, v104, v105, vcc
	v_fmamk_f32 v106, v83, 0x3a800000, v116
	v_mul_f32_e32 v107, 0x4b800000, v106
	v_cmp_gt_f32_e32 vcc, s3, v106
	s_nop 1
	v_cndmask_b32_e32 v106, v106, v107, vcc
	v_rsq_f32_e32 v106, v106
	s_nop 0
	v_mul_f32_e32 v107, 0x45800000, v106
	v_cndmask_b32_e32 v106, v106, v107, vcc
	v_lshlrev_b32_e32 v120, 16, v56
	v_and_b32_e32 v121, 0xffff0000, v56
	v_lshlrev_b32_e32 v122, 16, v57
	v_and_b32_e32 v123, 0xffff0000, v57
	v_lshlrev_b32_e32 v150, 16, v72
	v_and_b32_e32 v151, 0xffff0000, v72
	v_lshlrev_b32_e32 v152, 16, v73
	v_and_b32_e32 v153, 0xffff0000, v73
	v_pk_mul_f32 v[120:121], v[104:105], v[120:121] op_sel_hi:[0,1]
	v_pk_mul_f32 v[122:123], v[104:105], v[122:123] op_sel_hi:[0,1]
	v_pk_mul_f32 v[150:151], v[106:107], v[150:151] op_sel_hi:[0,1]
	v_pk_mul_f32 v[152:153], v[106:107], v[152:153] op_sel_hi:[0,1]
	v_pk_fma_f32 v[32:33], v[84:85], v[120:121], v[32:33]
	v_pk_fma_f32 v[34:35], v[86:87], v[122:123], v[34:35]
	v_pk_fma_f32 v[32:33], v[0:1], v[150:151], v[32:33]
	v_pk_fma_f32 v[34:35], v[2:3], v[152:153], v[34:35]
	v_lshlrev_b32_e32 v124, 16, v58
	v_and_b32_e32 v125, 0xffff0000, v58
	v_lshlrev_b32_e32 v126, 16, v59
	v_and_b32_e32 v127, 0xffff0000, v59
	v_lshlrev_b32_e32 v154, 16, v74
	v_and_b32_e32 v155, 0xffff0000, v74
	v_lshlrev_b32_e32 v156, 16, v75
	v_and_b32_e32 v157, 0xffff0000, v75
	v_pk_mul_f32 v[124:125], v[104:105], v[124:125] op_sel_hi:[0,1]
	v_pk_mul_f32 v[126:127], v[104:105], v[126:127] op_sel_hi:[0,1]
	v_pk_mul_f32 v[154:155], v[106:107], v[154:155] op_sel_hi:[0,1]
	v_pk_mul_f32 v[156:157], v[106:107], v[156:157] op_sel_hi:[0,1]
	v_pk_fma_f32 v[36:37], v[88:89], v[124:125], v[36:37]
	v_pk_fma_f32 v[38:39], v[90:91], v[126:127], v[38:39]
	v_pk_fma_f32 v[36:37], v[4:5], v[154:155], v[36:37]
	v_pk_fma_f32 v[38:39], v[6:7], v[156:157], v[38:39]
	v_lshlrev_b32_e32 v128, 16, v60
	v_and_b32_e32 v129, 0xffff0000, v60
	v_lshlrev_b32_e32 v130, 16, v61
	v_and_b32_e32 v131, 0xffff0000, v61
	v_lshlrev_b32_e32 v158, 16, v76
	v_and_b32_e32 v159, 0xffff0000, v76
	v_lshlrev_b32_e32 v160, 16, v77
	v_and_b32_e32 v161, 0xffff0000, v77
	v_pk_mul_f32 v[128:129], v[104:105], v[128:129] op_sel_hi:[0,1]
	v_pk_mul_f32 v[130:131], v[104:105], v[130:131] op_sel_hi:[0,1]
	v_pk_mul_f32 v[158:159], v[106:107], v[158:159] op_sel_hi:[0,1]
	v_pk_mul_f32 v[160:161], v[106:107], v[160:161] op_sel_hi:[0,1]
	v_pk_fma_f32 v[40:41], v[92:93], v[128:129], v[40:41]
	v_pk_fma_f32 v[42:43], v[94:95], v[130:131], v[42:43]
	v_pk_fma_f32 v[40:41], v[8:9], v[158:159], v[40:41]
	v_pk_fma_f32 v[42:43], v[10:11], v[160:161], v[42:43]
	v_lshlrev_b32_e32 v132, 16, v62
	v_and_b32_e32 v133, 0xffff0000, v62
	v_lshlrev_b32_e32 v134, 16, v63
	v_and_b32_e32 v135, 0xffff0000, v63
	v_lshlrev_b32_e32 v162, 16, v78
	v_and_b32_e32 v163, 0xffff0000, v78
	v_lshlrev_b32_e32 v164, 16, v79
	v_and_b32_e32 v165, 0xffff0000, v79
	v_pk_mul_f32 v[132:133], v[104:105], v[132:133] op_sel_hi:[0,1]
	v_pk_mul_f32 v[134:135], v[104:105], v[134:135] op_sel_hi:[0,1]
	v_pk_mul_f32 v[162:163], v[106:107], v[162:163] op_sel_hi:[0,1]
	v_pk_mul_f32 v[164:165], v[106:107], v[164:165] op_sel_hi:[0,1]
	v_pk_fma_f32 v[44:45], v[96:97], v[132:133], v[44:45]
	v_pk_fma_f32 v[46:47], v[98:99], v[134:135], v[46:47]
	v_pk_fma_f32 v[44:45], v[12:13], v[162:163], v[44:45]
	v_pk_fma_f32 v[46:47], v[14:15], v[164:165], v[46:47]
	global_store_dwordx4 v149, v[32:35], s[22:23] nt
	global_store_dwordx4 v149, v[36:39], s[22:23] offset:16 nt
	global_store_dwordx4 v149, v[40:43], s[22:23] offset:2048 nt
	global_store_dwordx4 v149, v[44:47], s[22:23] offset:2064 nt
	s_add_i32 s0, s0, s4
	s_add_u32 s20, s20, s98
	s_addc_u32 s21, s21, 0
	s_add_u32 s22, s22, s98
	s_addc_u32 s23, s23, 0
	s_add_u32 s24, s24, s99
	s_addc_u32 s25, s25, 0
	s_add_u32 s26, s26, s99
	s_addc_u32 s27, s27, 0
	s_add_u32 s16, s16, s100
	s_addc_u32 s17, s17, 0
	s_add_u32 s18, s18, s100
	s_addc_u32 s19, s19, 0
	s_cmpk_gt_i32 s0, 0x3fff
	s_cbranch_scc0 .Lxo_loop
